# NSA block-importance recompute: the four K-fragment loads of each compressed tile issued together with counted waits
# speedup vs baseline: 1.0333x; 1.0011x over previous
; #define MFMA(a, b, c) __builtin_amdgcn_mfma_f32_32x32x16_bf16((a), (b), (c), 0, 0, 0)
; DI float ex2(float x) { return __builtin_amdgcn_exp2f(x); }
; DI f32x16 zero16() { f32x16 z; _Pragma("unroll") for (int i = 0; i < 16; ++i) z[i] = 0.f; return z; }
; DI void fs_init(FS& s) { s.m = -1e30f; s.l = 0.f; s.o0 = zero16(); s.o1 = zero16(); }
; DI float sigmoidf_(float x) { return 1.f / (1.f + __expf(-x)); }
; DI void attn_unit(const Params& p, int l, int b, int qtp, int grp, char* smem) {
;     ...
;     const float g0 = sigmoidf_(gp[0]), g1 = sigmoidf_(gp[1]), g2 = sigmoidf_(gp[2]);
;     const bf16_t* kc = (const bf16_t*)(p.ws + OFF_KCMP) + (size_t)b * 128 * 64;
;     const bf16_t* vc = (const bf16_t*)(p.ws + OFF_VCMP) + (size_t)b * 64 * 128;
;     const int ktc = min(3, qt >> 4);
;     {
;       FS st; fs_init(st);
;       flash_direct<64, 16>(st, qf, kc, 64, vc, 128, 0, ktc, q0, qpos, 31, INFW, scale2, slope2, r, h);
;       const float lt = st.l + __shfl_xor(st.l, 32);
;       const float inv = lt > 0.f ? 1.f / lt : 0.f;
;       acc_store(accl, st.o0, st.o1, inv * g0);
;       float* impw = imp + (w * 32 + r) * 33;
;       for (int kt = 0; kt < 4; ++kt) {
;         if (kt <= ktc) {
;           const int key0 = kt * 32;
;           const bf16_t* kp = kc + (size_t)(key0 + r) * 64 + 8 * h;
;           f32x16 s = zero16();
; #pragma unroll
;           for (int ks = 0; ks < 4; ++ks) s = MFMA(*(const bf16x8*)(kp + 16 * ks), qf[ks], s);
;           const int dbase = qpos - 31 - 16 * (key0 + 4 * h);
;           const float zb = -slope2 * (float)dbase;
; #pragma unroll
;           for (int g = 0; g < 4; ++g) {
;             float sum4 = 0.f;
; #pragma unroll
;             for (int k = 0; k < 4; ++k) {
;               const int c = k + 8 * g;
;               const int dist = dbase - 16 * c;
;               const float zi = fmaf(s[4 * g + k], scale2, zb + slope2 * (float)(16 * c));
;               const float pi = (dist >= 0) ? ex2(zi - st.m) * inv : 0.f;
;               sum4 += pi;
;             }
;             impw[8 * kt + 2 * g + h] = sum4;
;           }
.LBB0_278:
	s_or_b64 exec, exec, s[2:3]
	s_waitcnt vmcnt(0)
	v_mul_f32_e32 v37, 0xbfb8aa3b, v148
	v_exp_f32_e32 v37, v37
	v_mul_i32_i24_e32 v36, 0x4200, v191
	v_mov_b32_e32 v121, v1
	v_lshlrev_b32_e32 v197, 2, v192
	v_add_f32_e32 v37, 1.0, v37
	v_div_scale_f32 v38, s[2:3], v37, v37, 1.0
	v_rcp_f32_e32 v39, v38
	v_mov_b32_e32 v167, v166
	v_fma_f32 v40, -v38, v39, 1.0
	v_fmac_f32_e32 v39, v40, v39
	v_div_scale_f32 v40, vcc, 1.0, v37, 1.0
	v_mul_f32_e32 v41, v40, v39
	v_fma_f32 v42, -v38, v41, v40
	v_fmac_f32_e32 v41, v42, v39
	v_fma_f32 v38, -v38, v41, v40
	v_div_fmas_f32 v38, v38, v39, v41
	v_cmp_lt_i32_e32 vcc, v159, v165
	v_div_fixup_f32 v37, v38, v37, 1.0
	s_nop 0
	v_cndmask_b32_e32 v38, v195, v159, vcc
	v_lshlrev_b32_e32 v148, 2, v38
	ds_bpermute_b32 v38, v148, v34
	s_waitcnt lgkmcnt(0)
	v_add_f32_e32 v34, v34, v38
	v_div_scale_f32 v38, s[4:5], v34, v34, 1.0
	v_rcp_f32_e32 v39, v38
	v_cmp_lt_f32_e64 s[2:3], 0, v34
	v_fma_f32 v40, -v38, v39, 1.0
	v_fmac_f32_e32 v39, v40, v39
	v_div_scale_f32 v40, vcc, 1.0, v34, 1.0
	v_mul_f32_e32 v41, v40, v39
	v_fma_f32 v42, -v38, v41, v40
	v_fmac_f32_e32 v41, v42, v39
	v_fma_f32 v38, -v38, v41, v40
	v_div_fmas_f32 v38, v38, v39, v41
	v_div_fixup_f32 v34, v38, v34, 1.0
	v_cndmask_b32_e64 v34, 0, v34, s[2:3]
	v_mul_f32_e32 v37, v37, v34
	v_mul_f32_e32 v18, v18, v37
	v_mul_f32_e32 v19, v19, v37
	v_mul_f32_e32 v3, v3, v37
	v_mul_f32_e32 v4, v4, v37
	ds_write2st64_b32 v218, v18, v19 offset0:138 offset1:146
	v_mul_f32_e32 v18, v20, v37
	ds_write2st64_b32 v161, v3, v4 offset0:136 offset1:144
	v_mul_f32_e32 v3, v21, v37
	ds_write2st64_b32 v218, v18, v3 offset0:154 offset1:162
	v_mul_f32_e32 v3, v5, v37
	v_mul_f32_e32 v5, v6, v37
	v_mul_f32_e32 v4, v22, v37
	ds_write2st64_b32 v161, v3, v5 offset0:152 offset1:160
	v_mul_f32_e32 v3, v23, v37
	ds_write2st64_b32 v218, v4, v3 offset0:170 offset1:178
	v_mul_f32_e32 v3, v7, v37
	v_mul_f32_e32 v5, v8, v37
	v_mul_f32_e32 v4, v24, v37
	ds_write2st64_b32 v161, v3, v5 offset0:168 offset1:176
	v_mul_f32_e32 v3, v25, v37
	ds_write2st64_b32 v218, v4, v3 offset0:186 offset1:194
	v_mul_f32_e32 v3, v9, v37
	v_mul_f32_e32 v5, v10, v37
	v_mul_f32_e32 v4, v26, v37
	ds_write2st64_b32 v161, v3, v5 offset0:184 offset1:192
	v_mul_f32_e32 v3, v27, v37
	ds_write2st64_b32 v218, v4, v3 offset0:202 offset1:210
	v_mul_f32_e32 v3, v11, v37
	v_mul_f32_e32 v5, v12, v37
	v_mul_f32_e32 v4, v28, v37
	ds_write2st64_b32 v161, v3, v5 offset0:200 offset1:208
	v_mul_f32_e32 v3, v29, v37
	ds_write2st64_b32 v218, v4, v3 offset0:218 offset1:226
	v_mul_f32_e32 v3, v13, v37
	v_mul_f32_e32 v5, v14, v37
	v_mul_f32_e32 v4, v30, v37
	ds_write2st64_b32 v161, v3, v5 offset0:216 offset1:224
	v_mul_f32_e32 v3, v31, v37
	ds_write2st64_b32 v218, v4, v3 offset0:234 offset1:242
	v_mul_f32_e32 v4, v32, v37
	v_mul_f32_e32 v3, v15, v37
	ds_write_b32 v218, v4 offset:64000
	v_mul_f32_e32 v4, v16, v37
	v_mul_f32_e32 v2, v2, v37
	ds_write2st64_b32 v161, v3, v4 offset0:232 offset1:240
	v_mul_f32_e32 v3, v33, v37
	ds_write2st64_b32 v161, v3, v2 offset0:120 offset1:128
	v_mul_f32_e32 v2, v17, v37
	ds_write_b32 v161, v2 offset:63488
	v_lshl_or_b32 v2, v151, 5, v190
	v_mul_u32_u24_e32 v2, 0x84, v2
	v_lshl_add_u64 v[18:19], s[0:1], 0, v[120:121]
	v_add3_u32 v20, v36, v2, v197
	v_cmp_lt_i32_e32 vcc, -1, v130
	s_and_saveexec_b64 s[0:1], vcc
	s_xor_b64 s[0:1], exec, s[0:1]
	s_cbranch_execz .LBB0_280
	v_lshl_add_u64 v[26:27], v[0:1], 1, v[18:19]
	global_load_dwordx4 v[2:5], v[26:27], off
	global_load_dwordx4 v[22:25], v[26:27], off offset:32
	global_load_dwordx4 v[248:251], v[26:27], off offset:64
	global_load_dwordx4 v[252:255], v[26:27], off offset:96
	v_sub_u32_e32 v21, v128, v129
	v_cmp_lt_i32_e32 vcc, -1, v21
	s_movk_i32 s2, 0xff
	s_waitcnt vmcnt(3)
	v_mfma_f32_32x32x16_bf16 v[2:17], v[2:5], v[96:99], 0
	s_waitcnt vmcnt(2)
	v_mfma_f32_32x32x16_bf16 v[2:17], v[22:25], v[100:103], v[2:17]
	s_nop 0
	s_waitcnt vmcnt(1)
	v_mfma_f32_32x32x16_bf16 v[2:17], v[248:251], v[104:107], v[2:17]
	s_nop 0
	s_waitcnt vmcnt(0)
	v_mfma_f32_32x32x16_bf16 v[2:17], v[252:255], v[108:111], v[2:17]
	v_cvt_f32_i32_e32 v22, v21
	v_fma_f32 v23, -v166, v22, v168
	s_nop 9
	v_fmac_f32_e32 v23, 0x3e38aa3b, v2
	v_sub_f32_e32 v2, v23, v35
	v_fma_f32 v23, -v166, v22, v169
	v_fmac_f32_e32 v23, 0x3e38aa3b, v3
	v_exp_f32_e32 v2, v2
	v_sub_f32_e32 v3, v23, v35
	v_exp_f32_e32 v3, v3
	v_fma_f32 v2, v34, v2, 0
	v_cndmask_b32_e32 v2, 0, v2, vcc
	v_mul_f32_e32 v3, v34, v3
	v_cmp_lt_i32_e32 vcc, 15, v21
	s_nop 1
	v_cndmask_b32_e32 v3, 0, v3, vcc
	v_add_f32_e32 v2, v3, v2
	v_fma_f32 v3, -v166, v22, v118
	v_fmac_f32_e32 v3, 0x3e38aa3b, v4
	v_sub_f32_e32 v3, v3, v35
	v_exp_f32_e32 v3, v3
	v_cmp_lt_i32_e32 vcc, 31, v21
	v_mul_f32_e32 v3, v34, v3
	s_nop 0
	v_cndmask_b32_e32 v3, 0, v3, vcc
	v_add_f32_e32 v2, v3, v2
	v_fma_f32 v3, -v166, v22, v119
	v_fmac_f32_e32 v3, 0x3e38aa3b, v5
	v_sub_f32_e32 v3, v3, v35
	v_exp_f32_e32 v3, v3
	v_cmp_lt_i32_e32 vcc, 47, v21
	v_fma_f32 v5, -v166, v22, v113
	v_fmac_f32_e32 v5, 0x3e38aa3b, v11
	v_mul_f32_e32 v3, v34, v3
	v_cndmask_b32_e32 v3, 0, v3, vcc
	v_add_f32_e32 v2, v3, v2
	v_fma_f32 v3, -v166, v22, v117
	v_fmac_f32_e32 v3, 0x3e38aa3b, v7
	v_sub_f32_e32 v3, v3, v35
	v_exp_f32_e32 v4, v3
	v_fma_f32 v3, -v166, v22, v114
	v_fmac_f32_e32 v3, 0x3e38aa3b, v8
	ds_write_b32 v20, v2
	v_fma_f32 v2, -v166, v22, v116
	v_sub_f32_e32 v3, v3, v35
	v_fmac_f32_e32 v2, 0x3e38aa3b, v6
	v_exp_f32_e32 v6, v3
	v_fma_f32 v3, -v166, v22, v115
	v_fmac_f32_e32 v3, 0x3e38aa3b, v9
	v_sub_f32_e32 v3, v3, v35
	v_exp_f32_e32 v8, v3
	v_fma_f32 v3, -v166, v22, v112
	v_fmac_f32_e32 v3, 0x3e38aa3b, v10
	v_sub_f32_e32 v2, v2, v35
	v_sub_f32_e32 v3, v3, v35
	v_exp_f32_e32 v2, v2
; #define MFMA(a, b, c) __builtin_amdgcn_mfma_f32_32x32x16_bf16((a), (b), (c), 0, 0, 0)
; DI float ex2(float x) { return __builtin_amdgcn_exp2f(x); }
; DI f32x16 zero16() { f32x16 z; _Pragma("unroll") for (int i = 0; i < 16; ++i) z[i] = 0.f; return z; }
; DI void attn_unit(const Params& p, int l, int b, int qtp, int grp, char* smem) {
;     ...
;       for (int kt = 0; kt < 4; ++kt) {
;         if (kt <= ktc) {
;           const int key0 = kt * 32;
;           const bf16_t* kp = kc + (size_t)(key0 + r) * 64 + 8 * h;
;           f32x16 s = zero16();
; #pragma unroll
;           for (int ks = 0; ks < 4; ++ks) s = MFMA(*(const bf16x8*)(kp + 16 * ks), qf[ks], s);
;           const int dbase = qpos - 31 - 16 * (key0 + 4 * h);
;           const float zb = -slope2 * (float)dbase;
; #pragma unroll
;           for (int g = 0; g < 4; ++g) {
;             float sum4 = 0.f;
; #pragma unroll
;             for (int k = 0; k < 4; ++k) {
;               const int c = k + 8 * g;
;               const int dist = dbase - 16 * c;
;               const float zi = fmaf(s[4 * g + k], scale2, zb + slope2 * (float)(16 * c));
;               const float pi = (dist >= 0) ? ex2(zi - st.m) * inv : 0.f;
;               sum4 += pi;
;             }
;             impw[8 * kt + 2 * g + h] = sum4;
;           }
;         } else {
; #pragma unroll
;           for (int g = 0; g < 4; ++g) impw[8 * kt + 2 * g + h] = 0.f;
	v_exp_f32_e32 v3, v3
	v_sub_f32_e32 v5, v5, v35
	v_exp_f32_e32 v5, v5
	v_fma_f32 v7, -v166, v22, v94
	v_fmac_f32_e32 v7, 0x3e38aa3b, v12
	v_sub_f32_e32 v7, v7, v35
	v_pk_fma_f32 v[2:3], v[34:35], v[2:3], 0 op_sel_hi:[0,1,0]
	v_cmp_lt_i32_e32 vcc, s2, v21
	s_movk_i32 s2, 0x7f
	v_exp_f32_e32 v7, v7
	v_fma_f32 v9, -v166, v22, v95
	v_cndmask_b32_e32 v3, 0, v3, vcc
	v_cmp_lt_i32_e32 vcc, s2, v21
	s_movk_i32 s2, 0x10f
	v_fmac_f32_e32 v9, 0x3e38aa3b, v13
	v_cndmask_b32_e32 v2, 0, v2, vcc
	v_pk_mul_f32 v[4:5], v[34:35], v[4:5] op_sel_hi:[0,1]
	v_cmp_lt_i32_e32 vcc, s2, v21
	s_movk_i32 s2, 0x8f
	v_sub_f32_e32 v9, v9, v35
	v_cndmask_b32_e32 v5, 0, v5, vcc
	v_cmp_lt_i32_e32 vcc, s2, v21
	v_exp_f32_e32 v9, v9
	s_movk_i32 s2, 0x11f
	v_cndmask_b32_e32 v4, 0, v4, vcc
	v_pk_add_f32 v[2:3], v[4:5], v[2:3]
	v_pk_mul_f32 v[4:5], v[34:35], v[6:7] op_sel_hi:[0,1]
	v_cmp_lt_i32_e32 vcc, s2, v21
	s_movk_i32 s2, 0x9f
	s_nop 0
	v_cndmask_b32_e32 v5, 0, v5, vcc
	v_cmp_lt_i32_e32 vcc, s2, v21
	s_movk_i32 s2, 0x12f
	s_nop 0
	v_cndmask_b32_e32 v4, 0, v4, vcc
	v_pk_add_f32 v[2:3], v[4:5], v[2:3]
	v_pk_mul_f32 v[4:5], v[34:35], v[8:9] op_sel_hi:[0,1]
	v_cmp_lt_i32_e32 vcc, s2, v21
	s_movk_i32 s2, 0xaf
	s_nop 0
	v_cndmask_b32_e32 v5, 0, v5, vcc
	v_cmp_lt_i32_e32 vcc, s2, v21
	s_movk_i32 s2, 0x17f
	s_nop 0
	v_cndmask_b32_e32 v4, 0, v4, vcc
	v_pk_add_f32 v[2:3], v[4:5], v[2:3]
	v_fma_f32 v4, -v166, v22, v92
	v_fmac_f32_e32 v4, 0x3e38aa3b, v14
	v_fma_f32 v5, -v166, v22, v93
	v_sub_f32_e32 v4, v4, v35
	v_fmac_f32_e32 v5, 0x3e38aa3b, v15
	v_exp_f32_e32 v4, v4
	v_sub_f32_e32 v5, v5, v35
	v_exp_f32_e32 v5, v5
	v_cmp_lt_i32_e32 vcc, s2, v21
	v_fma_f32 v4, v34, v4, 0
	s_movk_i32 s2, 0x18f
	v_cndmask_b32_e32 v4, 0, v4, vcc
	v_mul_f32_e32 v5, v34, v5
	v_cmp_lt_i32_e32 vcc, s2, v21
	s_movk_i32 s2, 0x19f
	s_nop 0
	v_cndmask_b32_e32 v5, 0, v5, vcc
	v_add_f32_e32 v4, v5, v4
	v_fma_f32 v5, -v166, v22, v90
	v_fmac_f32_e32 v5, 0x3e38aa3b, v16
	v_sub_f32_e32 v5, v5, v35
	v_exp_f32_e32 v5, v5
	v_cmp_lt_i32_e32 vcc, s2, v21
	s_movk_i32 s2, 0x1af
	v_mul_f32_e32 v5, v34, v5
	v_cndmask_b32_e32 v5, 0, v5, vcc
	v_add_f32_e32 v4, v5, v4
	v_fma_f32 v5, -v166, v22, v91
	v_fmac_f32_e32 v5, 0x3e38aa3b, v17
	v_sub_f32_e32 v5, v5, v35
	v_exp_f32_e32 v5, v5
	v_cmp_lt_i32_e32 vcc, s2, v21
	v_mul_f32_e32 v5, v34, v5
	s_nop 0
	v_cndmask_b32_e32 v5, 0, v5, vcc
	v_add_f32_e32 v4, v5, v4
.LBB0_280:
	s_andn2_saveexec_b64 s[0:1], s[0:1]
	v_mov_b32_e32 v4, 0
	v_mov_b32_e32 v2, 0
	v_mov_b32_e32 v3, 0
	ds_write_b32 v20, v1
	s_or_b64 exec, exec, s[0:1]
	v_cmp_lt_i32_e32 vcc, 0, v130
	ds_write2_b32 v20, v2, v3 offset0:2 offset1:4
	ds_write_b32 v20, v4 offset:24
	s_and_saveexec_b64 s[0:1], vcc
	s_xor_b64 s[0:1], exec, s[0:1]
	s_cbranch_execz .LBB0_284
	v_lshl_add_u64 v[2:3], v[0:1], 1, v[18:19]
	v_add_co_u32_e32 v26, vcc, 0x1000, v2
	v_or_b32_e32 v21, 0x200, v129
	s_nop 0
	v_addc_co_u32_e32 v27, vcc, 0, v3, vcc
	global_load_dwordx4 v[2:5], v[26:27], off
	global_load_dwordx4 v[22:25], v[26:27], off offset:32
	global_load_dwordx4 v[248:251], v[26:27], off offset:64
	global_load_dwordx4 v[252:255], v[26:27], off offset:96
	v_sub_u32_e32 v21, v128, v21
	v_cmp_lt_i32_e32 vcc, -1, v21
	s_movk_i32 s2, 0xff
	s_waitcnt vmcnt(3)
	v_mfma_f32_32x32x16_bf16 v[2:17], v[2:5], v[96:99], 0
	s_waitcnt vmcnt(2)
	v_mfma_f32_32x32x16_bf16 v[2:17], v[22:25], v[100:103], v[2:17]
	s_nop 0
	s_waitcnt vmcnt(1)
	v_mfma_f32_32x32x16_bf16 v[2:17], v[248:251], v[104:107], v[2:17]
	s_nop 0
	s_waitcnt vmcnt(0)
	v_mfma_f32_32x32x16_bf16 v[2:17], v[252:255], v[108:111], v[2:17]
	v_cvt_f32_i32_e32 v22, v21
	v_fma_f32 v23, -v166, v22, v168
	s_nop 9
	v_fmac_f32_e32 v23, 0x3e38aa3b, v2
	v_sub_f32_e32 v2, v23, v35
	v_fma_f32 v23, -v166, v22, v169
	v_fmac_f32_e32 v23, 0x3e38aa3b, v3
	v_exp_f32_e32 v2, v2
	v_sub_f32_e32 v3, v23, v35
	v_exp_f32_e32 v3, v3
	v_fma_f32 v2, v34, v2, 0
	v_cndmask_b32_e32 v2, 0, v2, vcc
	v_mul_f32_e32 v3, v34, v3
	v_cmp_lt_i32_e32 vcc, 15, v21
	s_nop 1
	v_cndmask_b32_e32 v3, 0, v3, vcc
	v_add_f32_e32 v2, v3, v2
	v_fma_f32 v3, -v166, v22, v118
	v_fmac_f32_e32 v3, 0x3e38aa3b, v4
	v_sub_f32_e32 v3, v3, v35
	v_exp_f32_e32 v3, v3
	v_cmp_lt_i32_e32 vcc, 31, v21
	v_mul_f32_e32 v3, v34, v3
	s_nop 0
	v_cndmask_b32_e32 v3, 0, v3, vcc
	v_add_f32_e32 v2, v3, v2
	v_fma_f32 v3, -v166, v22, v119
	v_fmac_f32_e32 v3, 0x3e38aa3b, v5
	v_sub_f32_e32 v3, v3, v35
	v_exp_f32_e32 v3, v3
	v_cmp_lt_i32_e32 vcc, 47, v21
	v_fma_f32 v5, -v166, v22, v113
	v_fmac_f32_e32 v5, 0x3e38aa3b, v11
	v_mul_f32_e32 v3, v34, v3
	v_cndmask_b32_e32 v3, 0, v3, vcc
	v_add_f32_e32 v2, v3, v2
	v_fma_f32 v3, -v166, v22, v117
	v_fmac_f32_e32 v3, 0x3e38aa3b, v7
	v_sub_f32_e32 v3, v3, v35
	v_exp_f32_e32 v4, v3
	v_fma_f32 v3, -v166, v22, v114
	v_fmac_f32_e32 v3, 0x3e38aa3b, v8
	ds_write_b32 v20, v2 offset:32
	v_fma_f32 v2, -v166, v22, v116
	v_sub_f32_e32 v3, v3, v35
	v_fmac_f32_e32 v2, 0x3e38aa3b, v6
	v_exp_f32_e32 v6, v3
	v_fma_f32 v3, -v166, v22, v115
	v_fmac_f32_e32 v3, 0x3e38aa3b, v9
	v_sub_f32_e32 v3, v3, v35
	v_exp_f32_e32 v8, v3
	v_fma_f32 v3, -v166, v22, v112
	v_fmac_f32_e32 v3, 0x3e38aa3b, v10
	v_sub_f32_e32 v2, v2, v35
	v_sub_f32_e32 v3, v3, v35
	v_exp_f32_e32 v2, v2
	v_exp_f32_e32 v3, v3
	v_sub_f32_e32 v5, v5, v35
	v_exp_f32_e32 v5, v5
	v_fma_f32 v7, -v166, v22, v94
	v_fmac_f32_e32 v7, 0x3e38aa3b, v12
	v_sub_f32_e32 v7, v7, v35
	v_pk_fma_f32 v[2:3], v[34:35], v[2:3], 0 op_sel_hi:[0,1,0]
	v_cmp_lt_i32_e32 vcc, s2, v21
	s_movk_i32 s2, 0x7f
	v_exp_f32_e32 v7, v7
	v_fma_f32 v9, -v166, v22, v95
	v_cndmask_b32_e32 v3, 0, v3, vcc
	v_cmp_lt_i32_e32 vcc, s2, v21
	s_movk_i32 s2, 0x10f
	v_fmac_f32_e32 v9, 0x3e38aa3b, v13
	v_cndmask_b32_e32 v2, 0, v2, vcc
; #define MFMA(a, b, c) __builtin_amdgcn_mfma_f32_32x32x16_bf16((a), (b), (c), 0, 0, 0)
; DI float ex2(float x) { return __builtin_amdgcn_exp2f(x); }
; DI f32x16 zero16() { f32x16 z; _Pragma("unroll") for (int i = 0; i < 16; ++i) z[i] = 0.f; return z; }
; DI void attn_unit(const Params& p, int l, int b, int qtp, int grp, char* smem) {
;     ...
;       for (int kt = 0; kt < 4; ++kt) {
;         if (kt <= ktc) {
;           const int key0 = kt * 32;
;           const bf16_t* kp = kc + (size_t)(key0 + r) * 64 + 8 * h;
;           f32x16 s = zero16();
; #pragma unroll
;           for (int ks = 0; ks < 4; ++ks) s = MFMA(*(const bf16x8*)(kp + 16 * ks), qf[ks], s);
;           const int dbase = qpos - 31 - 16 * (key0 + 4 * h);
;           const float zb = -slope2 * (float)dbase;
; #pragma unroll
;           for (int g = 0; g < 4; ++g) {
;             float sum4 = 0.f;
; #pragma unroll
;             for (int k = 0; k < 4; ++k) {
;               const int c = k + 8 * g;
;               const int dist = dbase - 16 * c;
;               const float zi = fmaf(s[4 * g + k], scale2, zb + slope2 * (float)(16 * c));
;               const float pi = (dist >= 0) ? ex2(zi - st.m) * inv : 0.f;
;               sum4 += pi;
;             }
;             impw[8 * kt + 2 * g + h] = sum4;
;           }
;         } else {
; #pragma unroll
;           for (int g = 0; g < 4; ++g) impw[8 * kt + 2 * g + h] = 0.f;
	v_pk_mul_f32 v[4:5], v[34:35], v[4:5] op_sel_hi:[0,1]
	v_cmp_lt_i32_e32 vcc, s2, v21
	s_movk_i32 s2, 0x8f
	v_sub_f32_e32 v9, v9, v35
	v_cndmask_b32_e32 v5, 0, v5, vcc
	v_cmp_lt_i32_e32 vcc, s2, v21
	v_exp_f32_e32 v9, v9
	s_movk_i32 s2, 0x11f
	v_cndmask_b32_e32 v4, 0, v4, vcc
	v_pk_add_f32 v[2:3], v[4:5], v[2:3]
	v_pk_mul_f32 v[4:5], v[34:35], v[6:7] op_sel_hi:[0,1]
	v_cmp_lt_i32_e32 vcc, s2, v21
	s_movk_i32 s2, 0x9f
	s_nop 0
	v_cndmask_b32_e32 v5, 0, v5, vcc
	v_cmp_lt_i32_e32 vcc, s2, v21
	s_movk_i32 s2, 0x12f
	s_nop 0
	v_cndmask_b32_e32 v4, 0, v4, vcc
	v_pk_add_f32 v[2:3], v[4:5], v[2:3]
	v_pk_mul_f32 v[4:5], v[34:35], v[8:9] op_sel_hi:[0,1]
	v_cmp_lt_i32_e32 vcc, s2, v21
	s_movk_i32 s2, 0xaf
	s_nop 0
	v_cndmask_b32_e32 v5, 0, v5, vcc
	v_cmp_lt_i32_e32 vcc, s2, v21
	s_movk_i32 s2, 0x17f
	s_nop 0
	v_cndmask_b32_e32 v4, 0, v4, vcc
	v_pk_add_f32 v[2:3], v[4:5], v[2:3]
	v_fma_f32 v4, -v166, v22, v92
	v_fmac_f32_e32 v4, 0x3e38aa3b, v14
	v_fma_f32 v5, -v166, v22, v93
	v_sub_f32_e32 v4, v4, v35
	v_fmac_f32_e32 v5, 0x3e38aa3b, v15
	v_exp_f32_e32 v4, v4
	v_sub_f32_e32 v5, v5, v35
	v_exp_f32_e32 v5, v5
	v_cmp_lt_i32_e32 vcc, s2, v21
	v_fma_f32 v4, v34, v4, 0
	s_movk_i32 s2, 0x18f
	v_cndmask_b32_e32 v4, 0, v4, vcc
	v_mul_f32_e32 v5, v34, v5
	v_cmp_lt_i32_e32 vcc, s2, v21
	s_movk_i32 s2, 0x19f
	s_nop 0
	v_cndmask_b32_e32 v5, 0, v5, vcc
	v_add_f32_e32 v4, v5, v4
	v_fma_f32 v5, -v166, v22, v90
	v_fmac_f32_e32 v5, 0x3e38aa3b, v16
	v_sub_f32_e32 v5, v5, v35
	v_exp_f32_e32 v5, v5
	v_cmp_lt_i32_e32 vcc, s2, v21
	s_movk_i32 s2, 0x1af
	v_mul_f32_e32 v5, v34, v5
	v_cndmask_b32_e32 v5, 0, v5, vcc
	v_add_f32_e32 v4, v5, v4
	v_fma_f32 v5, -v166, v22, v91
	v_fmac_f32_e32 v5, 0x3e38aa3b, v17
	v_sub_f32_e32 v5, v5, v35
	v_exp_f32_e32 v5, v5
	v_cmp_lt_i32_e32 vcc, s2, v21
	v_mul_f32_e32 v5, v34, v5
	s_nop 0
	v_cndmask_b32_e32 v5, 0, v5, vcc
	v_add_f32_e32 v4, v5, v4
.LBB0_284:
	s_andn2_saveexec_b64 s[0:1], s[0:1]
	v_mov_b32_e32 v4, 0
	v_mov_b32_e32 v2, 0
	v_mov_b32_e32 v3, v4
	ds_write_b32 v20, v1 offset:32
	s_or_b64 exec, exec, s[0:1]
	v_cmp_lt_i32_e32 vcc, 1, v130
	ds_write2_b32 v20, v2, v3 offset0:10 offset1:12
	ds_write_b32 v20, v4 offset:56
	s_and_saveexec_b64 s[0:1], vcc
	s_xor_b64 s[0:1], exec, s[0:1]
	s_cbranch_execz .LBB0_288
	v_lshl_add_u64 v[2:3], v[0:1], 1, v[18:19]
	v_add_co_u32_e32 v26, vcc, 0x2000, v2
	v_or_b32_e32 v21, 0x400, v129
	s_nop 0
	v_addc_co_u32_e32 v27, vcc, 0, v3, vcc
	global_load_dwordx4 v[2:5], v[26:27], off
	global_load_dwordx4 v[22:25], v[26:27], off offset:32
	global_load_dwordx4 v[248:251], v[26:27], off offset:64
	global_load_dwordx4 v[252:255], v[26:27], off offset:96
	v_sub_u32_e32 v21, v128, v21
	v_cmp_lt_i32_e32 vcc, -1, v21
	s_movk_i32 s2, 0xff
	s_waitcnt vmcnt(3)
	v_mfma_f32_32x32x16_bf16 v[2:17], v[2:5], v[96:99], 0
	s_waitcnt vmcnt(2)
	v_mfma_f32_32x32x16_bf16 v[2:17], v[22:25], v[100:103], v[2:17]
	s_nop 0
	s_waitcnt vmcnt(1)
	v_mfma_f32_32x32x16_bf16 v[2:17], v[248:251], v[104:107], v[2:17]
	s_nop 0
	s_waitcnt vmcnt(0)
	v_mfma_f32_32x32x16_bf16 v[2:17], v[252:255], v[108:111], v[2:17]
	v_cvt_f32_i32_e32 v22, v21
	v_fma_f32 v23, -v166, v22, v168
	s_nop 9
	v_fmac_f32_e32 v23, 0x3e38aa3b, v2
	v_sub_f32_e32 v2, v23, v35
	v_fma_f32 v23, -v166, v22, v169
	v_fmac_f32_e32 v23, 0x3e38aa3b, v3
	v_exp_f32_e32 v2, v2
	v_sub_f32_e32 v3, v23, v35
	v_exp_f32_e32 v3, v3
	v_fma_f32 v2, v34, v2, 0
	v_cndmask_b32_e32 v2, 0, v2, vcc
	v_mul_f32_e32 v3, v34, v3
	v_cmp_lt_i32_e32 vcc, 15, v21
	s_nop 1
	v_cndmask_b32_e32 v3, 0, v3, vcc
	v_add_f32_e32 v2, v3, v2
	v_fma_f32 v3, -v166, v22, v118
	v_fmac_f32_e32 v3, 0x3e38aa3b, v4
	v_sub_f32_e32 v3, v3, v35
	v_exp_f32_e32 v3, v3
	v_cmp_lt_i32_e32 vcc, 31, v21
	v_mul_f32_e32 v3, v34, v3
	s_nop 0
	v_cndmask_b32_e32 v3, 0, v3, vcc
	v_add_f32_e32 v2, v3, v2
	v_fma_f32 v3, -v166, v22, v119
	v_fmac_f32_e32 v3, 0x3e38aa3b, v5
	v_sub_f32_e32 v3, v3, v35
	v_exp_f32_e32 v3, v3
	v_cmp_lt_i32_e32 vcc, 47, v21
	v_fma_f32 v5, -v166, v22, v113
	v_fmac_f32_e32 v5, 0x3e38aa3b, v11
	v_mul_f32_e32 v3, v34, v3
	v_cndmask_b32_e32 v3, 0, v3, vcc
	v_add_f32_e32 v2, v3, v2
	v_fma_f32 v3, -v166, v22, v117
	v_fmac_f32_e32 v3, 0x3e38aa3b, v7
	v_sub_f32_e32 v3, v3, v35
	v_exp_f32_e32 v4, v3
	v_fma_f32 v3, -v166, v22, v114
	v_fmac_f32_e32 v3, 0x3e38aa3b, v8
	ds_write_b32 v20, v2 offset:64
	v_fma_f32 v2, -v166, v22, v116
	v_sub_f32_e32 v3, v3, v35
	v_fmac_f32_e32 v2, 0x3e38aa3b, v6
	v_exp_f32_e32 v6, v3
	v_fma_f32 v3, -v166, v22, v115
	v_fmac_f32_e32 v3, 0x3e38aa3b, v9
	v_sub_f32_e32 v3, v3, v35
	v_exp_f32_e32 v8, v3
	v_fma_f32 v3, -v166, v22, v112
	v_fmac_f32_e32 v3, 0x3e38aa3b, v10
	v_sub_f32_e32 v2, v2, v35
	v_sub_f32_e32 v3, v3, v35
	v_exp_f32_e32 v2, v2
	v_exp_f32_e32 v3, v3
	v_sub_f32_e32 v5, v5, v35
	v_exp_f32_e32 v5, v5
	v_fma_f32 v7, -v166, v22, v94
	v_fmac_f32_e32 v7, 0x3e38aa3b, v12
	v_sub_f32_e32 v7, v7, v35
	v_pk_fma_f32 v[2:3], v[34:35], v[2:3], 0 op_sel_hi:[0,1,0]
	v_cmp_lt_i32_e32 vcc, s2, v21
	s_movk_i32 s2, 0x7f
	v_exp_f32_e32 v7, v7
	v_fma_f32 v9, -v166, v22, v95
	v_cndmask_b32_e32 v3, 0, v3, vcc
	v_cmp_lt_i32_e32 vcc, s2, v21
	s_movk_i32 s2, 0x10f
	v_fmac_f32_e32 v9, 0x3e38aa3b, v13
	v_cndmask_b32_e32 v2, 0, v2, vcc
	v_pk_mul_f32 v[4:5], v[34:35], v[4:5] op_sel_hi:[0,1]
	v_cmp_lt_i32_e32 vcc, s2, v21
	s_movk_i32 s2, 0x8f
	v_sub_f32_e32 v9, v9, v35
	v_cndmask_b32_e32 v5, 0, v5, vcc
	v_cmp_lt_i32_e32 vcc, s2, v21
	v_exp_f32_e32 v9, v9
	s_movk_i32 s2, 0x11f
	v_cndmask_b32_e32 v4, 0, v4, vcc
	v_pk_add_f32 v[2:3], v[4:5], v[2:3]
	v_pk_mul_f32 v[4:5], v[34:35], v[6:7] op_sel_hi:[0,1]
	v_cmp_lt_i32_e32 vcc, s2, v21
	s_movk_i32 s2, 0x9f
	s_nop 0
	v_cndmask_b32_e32 v5, 0, v5, vcc
	v_cmp_lt_i32_e32 vcc, s2, v21
	s_movk_i32 s2, 0x12f
	s_nop 0
	v_cndmask_b32_e32 v4, 0, v4, vcc
	v_pk_add_f32 v[2:3], v[4:5], v[2:3]
	v_pk_mul_f32 v[4:5], v[34:35], v[8:9] op_sel_hi:[0,1]
	v_cmp_lt_i32_e32 vcc, s2, v21
	s_movk_i32 s2, 0xaf
	s_nop 0
	v_cndmask_b32_e32 v5, 0, v5, vcc
	v_cmp_lt_i32_e32 vcc, s2, v21
	s_movk_i32 s2, 0x17f
	s_nop 0
	v_cndmask_b32_e32 v4, 0, v4, vcc
	v_pk_add_f32 v[2:3], v[4:5], v[2:3]
	v_fma_f32 v4, -v166, v22, v92
	v_fmac_f32_e32 v4, 0x3e38aa3b, v14
	v_fma_f32 v5, -v166, v22, v93
	v_sub_f32_e32 v4, v4, v35
	v_fmac_f32_e32 v5, 0x3e38aa3b, v15
	v_exp_f32_e32 v4, v4
	v_sub_f32_e32 v5, v5, v35
	v_exp_f32_e32 v5, v5
	v_cmp_lt_i32_e32 vcc, s2, v21
	v_fma_f32 v4, v34, v4, 0
	s_movk_i32 s2, 0x18f
	v_cndmask_b32_e32 v4, 0, v4, vcc
	v_mul_f32_e32 v5, v34, v5
	v_cmp_lt_i32_e32 vcc, s2, v21
	s_movk_i32 s2, 0x19f
	s_nop 0
	v_cndmask_b32_e32 v5, 0, v5, vcc
	v_add_f32_e32 v4, v5, v4
	v_fma_f32 v5, -v166, v22, v90
	v_fmac_f32_e32 v5, 0x3e38aa3b, v16
	v_sub_f32_e32 v5, v5, v35
	v_exp_f32_e32 v5, v5
	v_cmp_lt_i32_e32 vcc, s2, v21
	s_movk_i32 s2, 0x1af
	v_mul_f32_e32 v5, v34, v5
	v_cndmask_b32_e32 v5, 0, v5, vcc
	v_add_f32_e32 v4, v5, v4
	v_fma_f32 v5, -v166, v22, v91
	v_fmac_f32_e32 v5, 0x3e38aa3b, v17
	v_sub_f32_e32 v5, v5, v35
	v_exp_f32_e32 v5, v5
	v_cmp_lt_i32_e32 vcc, s2, v21
	v_mul_f32_e32 v5, v34, v5
	s_nop 0
	v_cndmask_b32_e32 v5, 0, v5, vcc
	v_add_f32_e32 v4, v5, v4
; #define MFMA(a, b, c) __builtin_amdgcn_mfma_f32_32x32x16_bf16((a), (b), (c), 0, 0, 0)
; DI float ex2(float x) { return __builtin_amdgcn_exp2f(x); }
; DI f32x16 zero16() { f32x16 z; _Pragma("unroll") for (int i = 0; i < 16; ++i) z[i] = 0.f; return z; }
; DI void attn_unit(const Params& p, int l, int b, int qtp, int grp, char* smem) {
;     ...
;       for (int kt = 0; kt < 4; ++kt) {
;         if (kt <= ktc) {
;           const int key0 = kt * 32;
;           const bf16_t* kp = kc + (size_t)(key0 + r) * 64 + 8 * h;
;           f32x16 s = zero16();
; #pragma unroll
;           for (int ks = 0; ks < 4; ++ks) s = MFMA(*(const bf16x8*)(kp + 16 * ks), qf[ks], s);
;           const int dbase = qpos - 31 - 16 * (key0 + 4 * h);
;           const float zb = -slope2 * (float)dbase;
; #pragma unroll
;           for (int g = 0; g < 4; ++g) {
;             float sum4 = 0.f;
; #pragma unroll
;             for (int k = 0; k < 4; ++k) {
;               const int c = k + 8 * g;
;               const int dist = dbase - 16 * c;
;               const float zi = fmaf(s[4 * g + k], scale2, zb + slope2 * (float)(16 * c));
;               const float pi = (dist >= 0) ? ex2(zi - st.m) * inv : 0.f;
;               sum4 += pi;
;             }
;             impw[8 * kt + 2 * g + h] = sum4;
;           }
;         } else {
; #pragma unroll
;           for (int g = 0; g < 4; ++g) impw[8 * kt + 2 * g + h] = 0.f;
.LBB0_288:
	s_andn2_saveexec_b64 s[0:1], s[0:1]
	v_mov_b32_e32 v4, 0
	v_mov_b32_e32 v2, 0
	v_mov_b32_e32 v3, v4
	ds_write_b32 v20, v1 offset:64
	s_or_b64 exec, exec, s[0:1]
	v_cmp_lt_i32_e32 vcc, 2, v130
	ds_write2_b32 v20, v2, v3 offset0:18 offset1:20
	ds_write_b32 v20, v4 offset:88
	s_and_saveexec_b64 s[0:1], vcc
	s_xor_b64 s[0:1], exec, s[0:1]
	s_cbranch_execz .LBB0_292
	v_lshl_add_u64 v[2:3], v[0:1], 1, v[18:19]
	v_add_co_u32_e32 v18, vcc, 0x3000, v2
	v_or_b32_e32 v0, 0x600, v129
	s_nop 0
	v_addc_co_u32_e32 v19, vcc, 0, v3, vcc
	global_load_dwordx4 v[2:5], v[18:19], off
	global_load_dwordx4 v[22:25], v[18:19], off offset:32
	global_load_dwordx4 v[248:251], v[18:19], off offset:64
	global_load_dwordx4 v[252:255], v[18:19], off offset:96
	v_sub_u32_e32 v0, v128, v0
	v_cmp_lt_i32_e32 vcc, -1, v0
	s_movk_i32 s2, 0xff
	s_waitcnt vmcnt(3)
	v_mfma_f32_32x32x16_bf16 v[2:17], v[2:5], v[96:99], 0
	s_waitcnt vmcnt(2)
	v_mfma_f32_32x32x16_bf16 v[2:17], v[22:25], v[100:103], v[2:17]
	s_nop 0
	s_waitcnt vmcnt(1)
	v_mfma_f32_32x32x16_bf16 v[2:17], v[248:251], v[104:107], v[2:17]
	s_nop 0
	v_cvt_f32_i32_e32 v18, v0
	v_fma_f32 v19, -v166, v18, v168
	s_waitcnt vmcnt(0)
	v_mfma_f32_32x32x16_bf16 v[2:17], v[252:255], v[108:111], v[2:17]
	s_nop 11
	v_fmac_f32_e32 v19, 0x3e38aa3b, v2
	v_sub_f32_e32 v2, v19, v35
	v_fma_f32 v19, -v166, v18, v169
	v_fmac_f32_e32 v19, 0x3e38aa3b, v3
	v_exp_f32_e32 v2, v2
	v_sub_f32_e32 v3, v19, v35
	v_exp_f32_e32 v3, v3
	v_fma_f32 v2, v34, v2, 0
	v_cndmask_b32_e32 v2, 0, v2, vcc
	v_mul_f32_e32 v3, v34, v3
	v_cmp_lt_i32_e32 vcc, 15, v0
	s_nop 1
	v_cndmask_b32_e32 v3, 0, v3, vcc
	v_add_f32_e32 v2, v3, v2
	v_fma_f32 v3, -v166, v18, v118
	v_fmac_f32_e32 v3, 0x3e38aa3b, v4
	v_sub_f32_e32 v3, v3, v35
	v_exp_f32_e32 v3, v3
	v_cmp_lt_i32_e32 vcc, 31, v0
	v_mul_f32_e32 v3, v34, v3
	s_nop 0
	v_cndmask_b32_e32 v3, 0, v3, vcc
	v_add_f32_e32 v2, v3, v2
	v_fma_f32 v3, -v166, v18, v119
	v_fmac_f32_e32 v3, 0x3e38aa3b, v5
	v_sub_f32_e32 v3, v3, v35
	v_exp_f32_e32 v3, v3
	v_cmp_lt_i32_e32 vcc, 47, v0
	v_fma_f32 v5, -v166, v18, v113
	v_fmac_f32_e32 v5, 0x3e38aa3b, v11
	v_mul_f32_e32 v3, v34, v3
	v_cndmask_b32_e32 v3, 0, v3, vcc
	v_add_f32_e32 v2, v3, v2
	v_fma_f32 v3, -v166, v18, v117
	v_fmac_f32_e32 v3, 0x3e38aa3b, v7
	v_sub_f32_e32 v3, v3, v35
	v_exp_f32_e32 v4, v3
	v_fma_f32 v3, -v166, v18, v114
	v_fmac_f32_e32 v3, 0x3e38aa3b, v8
	ds_write_b32 v20, v2 offset:96
	v_fma_f32 v2, -v166, v18, v116
	v_sub_f32_e32 v3, v3, v35
	v_fmac_f32_e32 v2, 0x3e38aa3b, v6
	v_exp_f32_e32 v6, v3
	v_fma_f32 v3, -v166, v18, v115
	v_fmac_f32_e32 v3, 0x3e38aa3b, v9
	v_sub_f32_e32 v3, v3, v35
	v_exp_f32_e32 v8, v3
	v_fma_f32 v3, -v166, v18, v112
	v_fmac_f32_e32 v3, 0x3e38aa3b, v10
	v_sub_f32_e32 v2, v2, v35
	v_sub_f32_e32 v3, v3, v35
	v_exp_f32_e32 v2, v2
	v_exp_f32_e32 v3, v3
	v_sub_f32_e32 v5, v5, v35
	v_exp_f32_e32 v5, v5
	v_fma_f32 v7, -v166, v18, v94
	v_fmac_f32_e32 v7, 0x3e38aa3b, v12
	v_sub_f32_e32 v7, v7, v35
	v_pk_fma_f32 v[2:3], v[34:35], v[2:3], 0 op_sel_hi:[0,1,0]
	v_cmp_lt_i32_e32 vcc, s2, v0
	s_movk_i32 s2, 0x7f
	v_exp_f32_e32 v7, v7
	v_fma_f32 v9, -v166, v18, v95
	v_cndmask_b32_e32 v3, 0, v3, vcc
	v_cmp_lt_i32_e32 vcc, s2, v0
	s_movk_i32 s2, 0x10f
	v_fmac_f32_e32 v9, 0x3e38aa3b, v13
	v_cndmask_b32_e32 v2, 0, v2, vcc
	v_pk_mul_f32 v[4:5], v[34:35], v[4:5] op_sel_hi:[0,1]
	v_cmp_lt_i32_e32 vcc, s2, v0
	s_movk_i32 s2, 0x8f
	v_sub_f32_e32 v9, v9, v35
	v_cndmask_b32_e32 v5, 0, v5, vcc
	v_cmp_lt_i32_e32 vcc, s2, v0
	v_exp_f32_e32 v9, v9
	s_movk_i32 s2, 0x11f
	v_cndmask_b32_e32 v4, 0, v4, vcc
	v_pk_add_f32 v[2:3], v[4:5], v[2:3]
	v_pk_mul_f32 v[4:5], v[34:35], v[6:7] op_sel_hi:[0,1]
	v_cmp_lt_i32_e32 vcc, s2, v0
	s_movk_i32 s2, 0x9f
	s_nop 0
	v_cndmask_b32_e32 v5, 0, v5, vcc
	v_cmp_lt_i32_e32 vcc, s2, v0
	s_movk_i32 s2, 0x12f
	s_nop 0
	v_cndmask_b32_e32 v4, 0, v4, vcc
	v_pk_add_f32 v[2:3], v[4:5], v[2:3]
	v_pk_mul_f32 v[4:5], v[34:35], v[8:9] op_sel_hi:[0,1]
	v_cmp_lt_i32_e32 vcc, s2, v0
	s_movk_i32 s2, 0xaf
	s_nop 0
	v_cndmask_b32_e32 v5, 0, v5, vcc
	v_cmp_lt_i32_e32 vcc, s2, v0
	s_movk_i32 s2, 0x17f
	s_nop 0
	v_cndmask_b32_e32 v4, 0, v4, vcc
	v_pk_add_f32 v[2:3], v[4:5], v[2:3]
	v_fma_f32 v4, -v166, v18, v92
	v_fmac_f32_e32 v4, 0x3e38aa3b, v14
	v_fma_f32 v5, -v166, v18, v93
	v_sub_f32_e32 v4, v4, v35
	v_fmac_f32_e32 v5, 0x3e38aa3b, v15
	v_exp_f32_e32 v4, v4
	v_sub_f32_e32 v5, v5, v35
	v_exp_f32_e32 v5, v5
	v_cmp_lt_i32_e32 vcc, s2, v0
	v_fma_f32 v4, v34, v4, 0
	s_movk_i32 s2, 0x18f
	v_cndmask_b32_e32 v4, 0, v4, vcc
	v_mul_f32_e32 v5, v34, v5
	v_cmp_lt_i32_e32 vcc, s2, v0
	s_movk_i32 s2, 0x19f
	s_nop 0
	v_cndmask_b32_e32 v5, 0, v5, vcc
	v_add_f32_e32 v4, v5, v4
	v_fma_f32 v5, -v166, v18, v90
	v_fmac_f32_e32 v5, 0x3e38aa3b, v16
	v_sub_f32_e32 v5, v5, v35
	v_exp_f32_e32 v5, v5
	v_cmp_lt_i32_e32 vcc, s2, v0
	s_movk_i32 s2, 0x1af
	v_mul_f32_e32 v5, v34, v5
	v_cndmask_b32_e32 v5, 0, v5, vcc
	v_add_f32_e32 v4, v5, v4
	v_fma_f32 v5, -v166, v18, v91
	v_fmac_f32_e32 v5, 0x3e38aa3b, v17
	v_sub_f32_e32 v5, v5, v35
	v_exp_f32_e32 v5, v5
	v_cmp_lt_i32_e32 vcc, s2, v0
	v_mul_f32_e32 v5, v34, v5
	s_nop 0
	v_cndmask_b32_e32 v0, 0, v5, vcc
	v_add_f32_e32 v4, v0, v4

; __global__ void __launch_bounds__(512, 2) mega(Params p) {
;   __shared__ __attribute__((aligned(16))) char smem[163328];
	.amdhsa_kernel _Z4mega6Params
		.amdhsa_group_segment_fixed_size 163584
		.amdhsa_private_segment_fixed_size 0
		.amdhsa_kernarg_size 440
		.amdhsa_user_sgpr_count 2
		.amdhsa_user_sgpr_dispatch_ptr 0
		.amdhsa_user_sgpr_queue_ptr 0
		.amdhsa_user_sgpr_kernarg_segment_ptr 1
		.amdhsa_user_sgpr_dispatch_id 0
		.amdhsa_user_sgpr_kernarg_preload_length 0
		.amdhsa_user_sgpr_kernarg_preload_offset 0
		.amdhsa_user_sgpr_private_segment_size 0
		.amdhsa_uses_dynamic_stack 0
		.amdhsa_enable_private_segment 0
		.amdhsa_system_sgpr_workgroup_id_x 1
		.amdhsa_system_sgpr_workgroup_id_y 0
		.amdhsa_system_sgpr_workgroup_id_z 0
		.amdhsa_system_sgpr_workgroup_info 0
		.amdhsa_system_vgpr_workitem_id 2
		.amdhsa_next_free_vgpr 256
		.amdhsa_next_free_sgpr 100
		.amdhsa_accum_offset 256
		.amdhsa_reserve_vcc 1
		.amdhsa_float_round_mode_32 0
		.amdhsa_float_round_mode_16_64 0
		.amdhsa_float_denorm_mode_32 3
		.amdhsa_float_denorm_mode_16_64 3
		.amdhsa_dx10_clamp 1
		.amdhsa_ieee_mode 1
		.amdhsa_fp16_overflow 0
		.amdhsa_tg_split 0
		.amdhsa_exception_fp_ieee_invalid_op 0
		.amdhsa_exception_fp_denorm_src 0
		.amdhsa_exception_fp_ieee_div_zero 0
		.amdhsa_exception_fp_ieee_overflow 0
		.amdhsa_exception_fp_ieee_underflow 0
		.amdhsa_exception_fp_ieee_inexact 0
		.amdhsa_exception_int_div_zero 0
	.end_amdhsa_kernel

; __global__ void __launch_bounds__(512, 2) mega(Params p) {
;   __shared__ __attribute__((aligned(16))) char smem[163328];
amdhsa.kernels:
  - .agpr_count:     0
    .args:
      - .offset:         0
        .size:           184
        .value_kind:     by_value
      - .offset:         184
        .size:           4
        .value_kind:     hidden_block_count_x
      - .offset:         188
        .size:           4
        .value_kind:     hidden_block_count_y
      - .offset:         192
        .size:           4
        .value_kind:     hidden_block_count_z
      - .offset:         196
        .size:           2
        .value_kind:     hidden_group_size_x
      - .offset:         198
        .size:           2
        .value_kind:     hidden_group_size_y
      - .offset:         200
        .size:           2
        .value_kind:     hidden_group_size_z
      - .offset:         202
        .size:           2
        .value_kind:     hidden_remainder_x
      - .offset:         204
        .size:           2
        .value_kind:     hidden_remainder_y
      - .offset:         206
        .size:           2
        .value_kind:     hidden_remainder_z
      - .offset:         224
        .size:           8
        .value_kind:     hidden_global_offset_x
      - .offset:         232
        .size:           8
        .value_kind:     hidden_global_offset_y
      - .offset:         240
        .size:           8
        .value_kind:     hidden_global_offset_z
      - .offset:         248
        .size:           2
        .value_kind:     hidden_grid_dims
      - .offset:         272
        .size:           8
        .value_kind:     hidden_multigrid_sync_arg
    .group_segment_fixed_size: 163584
    .kernarg_segment_align: 8
    .kernarg_segment_size: 440
    .language:       OpenCL C
    .language_version:
      - 2
      - 0
    .max_flat_workgroup_size: 512
    .name:           _Z4mega6Params
    .private_segment_fixed_size: 0
    .sgpr_count:     106
    .sgpr_spill_count: 248
    .symbol:         _Z4mega6Params.kd
    .uniform_work_group_size: 1
    .uses_dynamic_stack: false
    .vgpr_count:     256
    .vgpr_spill_count: 0
    .wavefront_size: 64
